# ret_out epilogue: serialized gate load/store ladder replaced by 24-deep rolling window with counted vmcnt
# speedup vs baseline: 1.0056x; 1.0056x over previous
; __device__ __forceinline__ unsigned cvtpk(float lo, float hi) { return pg8::cvt_pk_bf16(lo, hi); }
;     ...
;         { R2_IDS const float rstd = 1.0f / sqrtf((ssp[32 * nt + r] + ssp[128 + 32 * nt + r]) * (1.0f / 512.0f) + RMS_EPS);
;           bf16* gp = GY + ((size_t)((bh >> 2) * SEQ + tq0 + 32 * nt + r)) * 2048 + h * 512 + 256 * eh + 4 * hh;
; #pragma unroll
;           for (int et = 0; et < 8; ++et)
; #pragma unroll
;               for (int i4 = 0; i4 < 4; ++i4) { bf16* p4 = gp + 32 * et + 8 * i4; const v2u gg = *(const v2u*)p4;
;                   v2u wv; wv.x = cvtpk(acc[et][4 * i4] * rstd * __uint_as_float(gg.x << 16), acc[et][4 * i4 + 1] * rstd * __uint_as_float(gg.x & 0xffff0000u));
;                   wv.y = cvtpk(acc[et][4 * i4 + 2] * rstd * __uint_as_float(gg.y << 16), acc[et][4 * i4 + 3] * rstd * __uint_as_float(gg.y & 0xffff0000u));
;                   if (!dry || rstd == 1.2345e38f) *(v2u*)p4 = wv; if (i4 == 3 && (et & 1)) asm volatile("" ::: "memory"); } }
.LBB0_717:
	s_or_b64 exec, exec, s[6:7]
	s_lshl_b32 s6, s36, 5
	s_and_b32 s6, s6, 0xffffe000
	v_mov_b32_e32 v52, v33
	s_add_i32 s5, s5, s6
	s_waitcnt lgkmcnt(0)
	s_barrier
	s_or_b32 s5, s5, s47
	s_waitcnt vmcnt(2)
	v_and_b32_e32 v56, 31, v52
	v_or_b32_e32 v50, s5, v56
	v_ashrrev_i32_e32 v51, 31, v50
	v_lshlrev_b64 v[50:51], 12, v[50:51]
	v_lshl_add_u64 v[50:51], s[28:29], 0, v[50:51]
	s_lshl_b32 s94, s4, 10
	v_lshl_add_u64 v[50:51], v[50:51], 0, s[94:95]
	v_lshrrev_b32_e32 v52, 2, v52
	v_lshl_add_u64 v[50:51], s[30:31], 1, v[50:51]
	v_and_b32_e32 v52, 8, v52
	v_mov_b32_e32 v53, v32
	v_lshl_add_u64 v[50:51], v[50:51], 0, v[52:53]
	global_load_dwordx2 v[82:83], v[50:51], off
	global_load_dwordx2 v[84:85], v[50:51], off offset:16
	global_load_dwordx2 v[86:87], v[50:51], off offset:32
	global_load_dwordx2 v[88:89], v[50:51], off offset:48
	global_load_dwordx2 v[90:91], v[50:51], off offset:64
	global_load_dwordx2 v[92:93], v[50:51], off offset:80
	global_load_dwordx2 v[204:205], v[50:51], off offset:96
	global_load_dwordx2 v[206:207], v[50:51], off offset:112
	global_load_dwordx2 v[208:209], v[50:51], off offset:128
	global_load_dwordx2 v[210:211], v[50:51], off offset:144
	global_load_dwordx2 v[212:213], v[50:51], off offset:160
	global_load_dwordx2 v[214:215], v[50:51], off offset:176
	global_load_dwordx2 v[216:217], v[50:51], off offset:192
	global_load_dwordx2 v[218:219], v[50:51], off offset:208
	global_load_dwordx2 v[220:221], v[50:51], off offset:224
	global_load_dwordx2 v[222:223], v[50:51], off offset:240
	global_load_dwordx2 v[224:225], v[50:51], off offset:256
	global_load_dwordx2 v[226:227], v[50:51], off offset:272
	global_load_dwordx2 v[238:239], v[50:51], off offset:288
	global_load_dwordx2 v[240:241], v[50:51], off offset:304
	global_load_dwordx2 v[242:243], v[50:51], off offset:320
	global_load_dwordx2 v[244:245], v[50:51], off offset:336
	global_load_dwordx2 v[246:247], v[50:51], off offset:352
	global_load_dwordx2 v[248:249], v[50:51], off offset:368
	v_lshl_add_u32 v52, v56, 2, s50
	ds_read2st64_b32 v[52:53], v52 offset1:2
	s_add_i32 s36, s36, s48
	s_cmpk_lt_i32 s36, 0x200
	s_waitcnt lgkmcnt(0)
	v_add_f32_e32 v52, v52, v53
	v_fmamk_f32 v52, v52, 0x3b000000, v231
	v_mul_f32_e32 v53, 0x4f800000, v52
	v_cmp_gt_f32_e32 vcc, s73, v52
	s_nop 1
	v_cndmask_b32_e32 v52, v52, v53, vcc
	v_sqrt_f32_e32 v53, v52
	s_nop 0
	v_add_u32_e32 v56, -1, v53
	v_add_u32_e32 v57, 1, v53
	v_fma_f32 v58, -v56, v53, v52
	v_fma_f32 v59, -v57, v53, v52
	v_cmp_ge_f32_e64 s[40:41], 0, v58
	s_nop 1
	v_cndmask_b32_e64 v53, v53, v56, s[40:41]
	v_cmp_lt_f32_e64 s[40:41], 0, v59
	s_nop 1
	v_cndmask_b32_e64 v53, v53, v57, s[40:41]
	v_mul_f32_e32 v56, 0x37800000, v53
	v_cndmask_b32_e32 v53, v53, v56, vcc
	v_cmp_class_f32_e32 vcc, v52, v232
	s_nop 1
	v_cndmask_b32_e32 v52, v53, v52, vcc
	v_div_scale_f32 v53, s[4:5], v52, v52, 1.0
	v_rcp_f32_e32 v56, v53
	v_div_scale_f32 v57, vcc, 1.0, v52, 1.0
	v_fma_f32 v58, -v53, v56, 1.0
	v_fmac_f32_e32 v56, v58, v56
	v_mul_f32_e32 v58, v57, v56
	v_fma_f32 v59, -v53, v58, v57
	v_fmac_f32_e32 v58, v59, v56
	v_fma_f32 v53, -v53, v58, v57
	v_div_fmas_f32 v53, v53, v56, v58
	v_div_fixup_f32 v52, v53, v52, 1.0
	s_waitcnt vmcnt(23)
	v_lshlrev_b32_e32 v57, 16, v82
	v_and_b32_e32 v58, 0xffff0000, v82
	v_lshlrev_b32_e32 v59, 16, v83
	v_and_b32_e32 v60, 0xffff0000, v83
	v_mul_f32_e32 v53, v178, v52
	v_mul_f32_e32 v54, v179, v52
	v_mul_f32_e32 v55, v180, v52
	v_mul_f32_e32 v56, v181, v52
	v_mul_f32_e32 v53, v53, v57
	v_mul_f32_e32 v54, v54, v58
	v_mul_f32_e32 v55, v55, v59
	v_mul_f32_e32 v56, v56, v60
	v_cvt_pk_bf16_f32 v250, v53, v54
	v_cvt_pk_bf16_f32 v251, v55, v56
	global_store_dwordx2 v[50:51], v[250:251], off
	global_load_dwordx2 v[82:83], v[50:51], off offset:384
	s_waitcnt vmcnt(24)
	v_lshlrev_b32_e32 v57, 16, v84
	v_and_b32_e32 v58, 0xffff0000, v84
	v_lshlrev_b32_e32 v59, 16, v85
	v_and_b32_e32 v60, 0xffff0000, v85
	v_mul_f32_e32 v53, v182, v52
	v_mul_f32_e32 v54, v183, v52
	v_mul_f32_e32 v55, v184, v52
	v_mul_f32_e32 v56, v185, v52
	v_mul_f32_e32 v53, v53, v57
	v_mul_f32_e32 v54, v54, v58
	v_mul_f32_e32 v55, v55, v59
	v_mul_f32_e32 v56, v56, v60
	v_cvt_pk_bf16_f32 v252, v53, v54
	v_cvt_pk_bf16_f32 v253, v55, v56
	global_store_dwordx2 v[50:51], v[252:253], off offset:16
	global_load_dwordx2 v[84:85], v[50:51], off offset:400
	s_waitcnt vmcnt(25)
	v_lshlrev_b32_e32 v57, 16, v86
	v_and_b32_e32 v58, 0xffff0000, v86
	v_lshlrev_b32_e32 v59, 16, v87
	v_and_b32_e32 v60, 0xffff0000, v87
	v_mul_f32_e32 v53, v186, v52
	v_mul_f32_e32 v54, v187, v52
	v_mul_f32_e32 v55, v188, v52
	v_mul_f32_e32 v56, v189, v52
	v_mul_f32_e32 v53, v53, v57
	v_mul_f32_e32 v54, v54, v58
	v_mul_f32_e32 v55, v55, v59
	v_mul_f32_e32 v56, v56, v60
	v_cvt_pk_bf16_f32 v250, v53, v54
	v_cvt_pk_bf16_f32 v251, v55, v56
	global_store_dwordx2 v[50:51], v[250:251], off offset:32
	global_load_dwordx2 v[86:87], v[50:51], off offset:416
	s_waitcnt vmcnt(26)
	v_lshlrev_b32_e32 v57, 16, v88
	v_and_b32_e32 v58, 0xffff0000, v88
	v_lshlrev_b32_e32 v59, 16, v89
	v_and_b32_e32 v60, 0xffff0000, v89
	v_mul_f32_e32 v53, v190, v52
	v_mul_f32_e32 v54, v191, v52
	v_mul_f32_e32 v55, v192, v52
	v_mul_f32_e32 v56, v193, v52
	v_mul_f32_e32 v53, v53, v57
	v_mul_f32_e32 v54, v54, v58
	v_mul_f32_e32 v55, v55, v59
	v_mul_f32_e32 v56, v56, v60
	v_cvt_pk_bf16_f32 v252, v53, v54
	v_cvt_pk_bf16_f32 v253, v55, v56
	global_store_dwordx2 v[50:51], v[252:253], off offset:48
	global_load_dwordx2 v[88:89], v[50:51], off offset:432
	s_waitcnt vmcnt(27)
; __device__ __forceinline__ unsigned cvtpk(float lo, float hi) { return pg8::cvt_pk_bf16(lo, hi); }
;     ...
;           for (int et = 0; et < 8; ++et)
; #pragma unroll
;               for (int i4 = 0; i4 < 4; ++i4) { bf16* p4 = gp + 32 * et + 8 * i4; const v2u gg = *(const v2u*)p4;
;                   v2u wv; wv.x = cvtpk(acc[et][4 * i4] * rstd * __uint_as_float(gg.x << 16), acc[et][4 * i4 + 1] * rstd * __uint_as_float(gg.x & 0xffff0000u));
;                   wv.y = cvtpk(acc[et][4 * i4 + 2] * rstd * __uint_as_float(gg.y << 16), acc[et][4 * i4 + 3] * rstd * __uint_as_float(gg.y & 0xffff0000u));
;                   if (!dry || rstd == 1.2345e38f) *(v2u*)p4 = wv; if (i4 == 3 && (et & 1)) asm volatile("" ::: "memory"); } }
	v_lshlrev_b32_e32 v57, 16, v90
	v_and_b32_e32 v58, 0xffff0000, v90
	v_lshlrev_b32_e32 v59, 16, v91
	v_and_b32_e32 v60, 0xffff0000, v91
	v_mul_f32_e32 v53, v162, v52
	v_mul_f32_e32 v54, v163, v52
	v_mul_f32_e32 v55, v164, v52
	v_mul_f32_e32 v56, v165, v52
	v_mul_f32_e32 v53, v53, v57
	v_mul_f32_e32 v54, v54, v58
	v_mul_f32_e32 v55, v55, v59
	v_mul_f32_e32 v56, v56, v60
	v_cvt_pk_bf16_f32 v250, v53, v54
	v_cvt_pk_bf16_f32 v251, v55, v56
	global_store_dwordx2 v[50:51], v[250:251], off offset:64
	global_load_dwordx2 v[90:91], v[50:51], off offset:448
	s_waitcnt vmcnt(28)
	v_lshlrev_b32_e32 v57, 16, v92
	v_and_b32_e32 v58, 0xffff0000, v92
	v_lshlrev_b32_e32 v59, 16, v93
	v_and_b32_e32 v60, 0xffff0000, v93
	v_mul_f32_e32 v53, v166, v52
	v_mul_f32_e32 v54, v167, v52
	v_mul_f32_e32 v55, v168, v52
	v_mul_f32_e32 v56, v169, v52
	v_mul_f32_e32 v53, v53, v57
	v_mul_f32_e32 v54, v54, v58
	v_mul_f32_e32 v55, v55, v59
	v_mul_f32_e32 v56, v56, v60
	v_cvt_pk_bf16_f32 v252, v53, v54
	v_cvt_pk_bf16_f32 v253, v55, v56
	global_store_dwordx2 v[50:51], v[252:253], off offset:80
	global_load_dwordx2 v[92:93], v[50:51], off offset:464
	s_waitcnt vmcnt(29)
	v_lshlrev_b32_e32 v57, 16, v204
	v_and_b32_e32 v58, 0xffff0000, v204
	v_lshlrev_b32_e32 v59, 16, v205
	v_and_b32_e32 v60, 0xffff0000, v205
	v_mul_f32_e32 v53, v170, v52
	v_mul_f32_e32 v54, v171, v52
	v_mul_f32_e32 v55, v172, v52
	v_mul_f32_e32 v56, v173, v52
	v_mul_f32_e32 v53, v53, v57
	v_mul_f32_e32 v54, v54, v58
	v_mul_f32_e32 v55, v55, v59
	v_mul_f32_e32 v56, v56, v60
	v_cvt_pk_bf16_f32 v250, v53, v54
	v_cvt_pk_bf16_f32 v251, v55, v56
	global_store_dwordx2 v[50:51], v[250:251], off offset:96
	global_load_dwordx2 v[204:205], v[50:51], off offset:480
	s_waitcnt vmcnt(30)
	v_lshlrev_b32_e32 v57, 16, v206
	v_and_b32_e32 v58, 0xffff0000, v206
	v_lshlrev_b32_e32 v59, 16, v207
	v_and_b32_e32 v60, 0xffff0000, v207
	v_mul_f32_e32 v53, v174, v52
	v_mul_f32_e32 v54, v175, v52
	v_mul_f32_e32 v55, v176, v52
	v_mul_f32_e32 v56, v177, v52
	v_mul_f32_e32 v53, v53, v57
	v_mul_f32_e32 v54, v54, v58
	v_mul_f32_e32 v55, v55, v59
	v_mul_f32_e32 v56, v56, v60
	v_cvt_pk_bf16_f32 v252, v53, v54
	v_cvt_pk_bf16_f32 v253, v55, v56
	global_store_dwordx2 v[50:51], v[252:253], off offset:112
	global_load_dwordx2 v[206:207], v[50:51], off offset:496
	s_waitcnt vmcnt(31)
	v_lshlrev_b32_e32 v57, 16, v208
	v_and_b32_e32 v58, 0xffff0000, v208
	v_lshlrev_b32_e32 v59, 16, v209
	v_and_b32_e32 v60, 0xffff0000, v209
	v_mul_f32_e32 v53, v146, v52
	v_mul_f32_e32 v54, v147, v52
	v_mul_f32_e32 v55, v148, v52
	v_mul_f32_e32 v56, v149, v52
	v_mul_f32_e32 v53, v53, v57
	v_mul_f32_e32 v54, v54, v58
	v_mul_f32_e32 v55, v55, v59
	v_mul_f32_e32 v56, v56, v60
	v_cvt_pk_bf16_f32 v250, v53, v54
	v_cvt_pk_bf16_f32 v251, v55, v56
	global_store_dwordx2 v[50:51], v[250:251], off offset:128
	s_waitcnt vmcnt(31)
	v_lshlrev_b32_e32 v57, 16, v210
	v_and_b32_e32 v58, 0xffff0000, v210
	v_lshlrev_b32_e32 v59, 16, v211
	v_and_b32_e32 v60, 0xffff0000, v211
	v_mul_f32_e32 v53, v150, v52
	v_mul_f32_e32 v54, v151, v52
	v_mul_f32_e32 v55, v152, v52
	v_mul_f32_e32 v56, v153, v52
	v_mul_f32_e32 v53, v53, v57
	v_mul_f32_e32 v54, v54, v58
	v_mul_f32_e32 v55, v55, v59
	v_mul_f32_e32 v56, v56, v60
	v_cvt_pk_bf16_f32 v252, v53, v54
	v_cvt_pk_bf16_f32 v253, v55, v56
	global_store_dwordx2 v[50:51], v[252:253], off offset:144
	s_waitcnt vmcnt(31)
	v_lshlrev_b32_e32 v57, 16, v212
	v_and_b32_e32 v58, 0xffff0000, v212
	v_lshlrev_b32_e32 v59, 16, v213
	v_and_b32_e32 v60, 0xffff0000, v213
	v_mul_f32_e32 v53, v154, v52
	v_mul_f32_e32 v54, v155, v52
	v_mul_f32_e32 v55, v156, v52
	v_mul_f32_e32 v56, v157, v52
	v_mul_f32_e32 v53, v53, v57
	v_mul_f32_e32 v54, v54, v58
	v_mul_f32_e32 v55, v55, v59
	v_mul_f32_e32 v56, v56, v60
	v_cvt_pk_bf16_f32 v250, v53, v54
	v_cvt_pk_bf16_f32 v251, v55, v56
	global_store_dwordx2 v[50:51], v[250:251], off offset:160
	s_waitcnt vmcnt(31)
	v_lshlrev_b32_e32 v57, 16, v214
	v_and_b32_e32 v58, 0xffff0000, v214
	v_lshlrev_b32_e32 v59, 16, v215
	v_and_b32_e32 v60, 0xffff0000, v215
	v_mul_f32_e32 v53, v158, v52
	v_mul_f32_e32 v54, v159, v52
	v_mul_f32_e32 v55, v160, v52
	v_mul_f32_e32 v56, v161, v52
	v_mul_f32_e32 v53, v53, v57
	v_mul_f32_e32 v54, v54, v58
	v_mul_f32_e32 v55, v55, v59
	v_mul_f32_e32 v56, v56, v60
	v_cvt_pk_bf16_f32 v252, v53, v54
	v_cvt_pk_bf16_f32 v253, v55, v56
	global_store_dwordx2 v[50:51], v[252:253], off offset:176
	s_waitcnt vmcnt(31)
	v_lshlrev_b32_e32 v57, 16, v216
	v_and_b32_e32 v58, 0xffff0000, v216
	v_lshlrev_b32_e32 v59, 16, v217
	v_and_b32_e32 v60, 0xffff0000, v217
	v_mul_f32_e32 v53, v130, v52
	v_mul_f32_e32 v54, v131, v52
	v_mul_f32_e32 v55, v132, v52
	v_mul_f32_e32 v56, v133, v52
	v_mul_f32_e32 v53, v53, v57
	v_mul_f32_e32 v54, v54, v58
	v_mul_f32_e32 v55, v55, v59
	v_mul_f32_e32 v56, v56, v60
	v_cvt_pk_bf16_f32 v250, v53, v54
	v_cvt_pk_bf16_f32 v251, v55, v56
	global_store_dwordx2 v[50:51], v[250:251], off offset:192
	s_waitcnt vmcnt(31)
	v_lshlrev_b32_e32 v57, 16, v218
	v_and_b32_e32 v58, 0xffff0000, v218
	v_lshlrev_b32_e32 v59, 16, v219
	v_and_b32_e32 v60, 0xffff0000, v219
	v_mul_f32_e32 v53, v134, v52
	v_mul_f32_e32 v54, v135, v52
	v_mul_f32_e32 v55, v136, v52
	v_mul_f32_e32 v56, v137, v52
	v_mul_f32_e32 v53, v53, v57
	v_mul_f32_e32 v54, v54, v58
	v_mul_f32_e32 v55, v55, v59
	v_mul_f32_e32 v56, v56, v60
	v_cvt_pk_bf16_f32 v252, v53, v54
	v_cvt_pk_bf16_f32 v253, v55, v56
	global_store_dwordx2 v[50:51], v[252:253], off offset:208
	s_waitcnt vmcnt(31)
; __device__ __forceinline__ unsigned cvtpk(float lo, float hi) { return pg8::cvt_pk_bf16(lo, hi); }
;     ...
;           for (int et = 0; et < 8; ++et)
; #pragma unroll
;               for (int i4 = 0; i4 < 4; ++i4) { bf16* p4 = gp + 32 * et + 8 * i4; const v2u gg = *(const v2u*)p4;
;                   v2u wv; wv.x = cvtpk(acc[et][4 * i4] * rstd * __uint_as_float(gg.x << 16), acc[et][4 * i4 + 1] * rstd * __uint_as_float(gg.x & 0xffff0000u));
;                   wv.y = cvtpk(acc[et][4 * i4 + 2] * rstd * __uint_as_float(gg.y << 16), acc[et][4 * i4 + 3] * rstd * __uint_as_float(gg.y & 0xffff0000u));
;                   if (!dry || rstd == 1.2345e38f) *(v2u*)p4 = wv; if (i4 == 3 && (et & 1)) asm volatile("" ::: "memory"); } }
	v_lshlrev_b32_e32 v57, 16, v220
	v_and_b32_e32 v58, 0xffff0000, v220
	v_lshlrev_b32_e32 v59, 16, v221
	v_and_b32_e32 v60, 0xffff0000, v221
	v_mul_f32_e32 v53, v138, v52
	v_mul_f32_e32 v54, v139, v52
	v_mul_f32_e32 v55, v140, v52
	v_mul_f32_e32 v56, v141, v52
	v_mul_f32_e32 v53, v53, v57
	v_mul_f32_e32 v54, v54, v58
	v_mul_f32_e32 v55, v55, v59
	v_mul_f32_e32 v56, v56, v60
	v_cvt_pk_bf16_f32 v250, v53, v54
	v_cvt_pk_bf16_f32 v251, v55, v56
	global_store_dwordx2 v[50:51], v[250:251], off offset:224
	s_waitcnt vmcnt(31)
	v_lshlrev_b32_e32 v57, 16, v222
	v_and_b32_e32 v58, 0xffff0000, v222
	v_lshlrev_b32_e32 v59, 16, v223
	v_and_b32_e32 v60, 0xffff0000, v223
	v_mul_f32_e32 v53, v142, v52
	v_mul_f32_e32 v54, v143, v52
	v_mul_f32_e32 v55, v144, v52
	v_mul_f32_e32 v56, v145, v52
	v_mul_f32_e32 v53, v53, v57
	v_mul_f32_e32 v54, v54, v58
	v_mul_f32_e32 v55, v55, v59
	v_mul_f32_e32 v56, v56, v60
	v_cvt_pk_bf16_f32 v252, v53, v54
	v_cvt_pk_bf16_f32 v253, v55, v56
	global_store_dwordx2 v[50:51], v[252:253], off offset:240
	s_waitcnt vmcnt(31)
	v_lshlrev_b32_e32 v57, 16, v224
	v_and_b32_e32 v58, 0xffff0000, v224
	v_lshlrev_b32_e32 v59, 16, v225
	v_and_b32_e32 v60, 0xffff0000, v225
	v_mul_f32_e32 v53, v66, v52
	v_mul_f32_e32 v54, v67, v52
	v_mul_f32_e32 v55, v68, v52
	v_mul_f32_e32 v56, v69, v52
	v_mul_f32_e32 v53, v53, v57
	v_mul_f32_e32 v54, v54, v58
	v_mul_f32_e32 v55, v55, v59
	v_mul_f32_e32 v56, v56, v60
	v_cvt_pk_bf16_f32 v250, v53, v54
	v_cvt_pk_bf16_f32 v251, v55, v56
	global_store_dwordx2 v[50:51], v[250:251], off offset:256
	s_waitcnt vmcnt(31)
	v_lshlrev_b32_e32 v57, 16, v226
	v_and_b32_e32 v58, 0xffff0000, v226
	v_lshlrev_b32_e32 v59, 16, v227
	v_and_b32_e32 v60, 0xffff0000, v227
	v_mul_f32_e32 v53, v70, v52
	v_mul_f32_e32 v54, v71, v52
	v_mul_f32_e32 v55, v72, v52
	v_mul_f32_e32 v56, v73, v52
	v_mul_f32_e32 v53, v53, v57
	v_mul_f32_e32 v54, v54, v58
	v_mul_f32_e32 v55, v55, v59
	v_mul_f32_e32 v56, v56, v60
	v_cvt_pk_bf16_f32 v252, v53, v54
	v_cvt_pk_bf16_f32 v253, v55, v56
	global_store_dwordx2 v[50:51], v[252:253], off offset:272
	s_waitcnt vmcnt(31)
	v_lshlrev_b32_e32 v57, 16, v238
	v_and_b32_e32 v58, 0xffff0000, v238
	v_lshlrev_b32_e32 v59, 16, v239
	v_and_b32_e32 v60, 0xffff0000, v239
	v_mul_f32_e32 v53, v74, v52
	v_mul_f32_e32 v54, v75, v52
	v_mul_f32_e32 v55, v76, v52
	v_mul_f32_e32 v56, v77, v52
	v_mul_f32_e32 v53, v53, v57
	v_mul_f32_e32 v54, v54, v58
	v_mul_f32_e32 v55, v55, v59
	v_mul_f32_e32 v56, v56, v60
	v_cvt_pk_bf16_f32 v250, v53, v54
	v_cvt_pk_bf16_f32 v251, v55, v56
	global_store_dwordx2 v[50:51], v[250:251], off offset:288
	s_waitcnt vmcnt(31)
	v_lshlrev_b32_e32 v57, 16, v240
	v_and_b32_e32 v58, 0xffff0000, v240
	v_lshlrev_b32_e32 v59, 16, v241
	v_and_b32_e32 v60, 0xffff0000, v241
	v_mul_f32_e32 v53, v78, v52
	v_mul_f32_e32 v54, v79, v52
	v_mul_f32_e32 v55, v80, v52
	v_mul_f32_e32 v56, v81, v52
	v_mul_f32_e32 v53, v53, v57
	v_mul_f32_e32 v54, v54, v58
	v_mul_f32_e32 v55, v55, v59
	v_mul_f32_e32 v56, v56, v60
	v_cvt_pk_bf16_f32 v252, v53, v54
	v_cvt_pk_bf16_f32 v253, v55, v56
	global_store_dwordx2 v[50:51], v[252:253], off offset:304
	s_waitcnt vmcnt(31)
	v_lshlrev_b32_e32 v57, 16, v242
	v_and_b32_e32 v58, 0xffff0000, v242
	v_lshlrev_b32_e32 v59, 16, v243
	v_and_b32_e32 v60, 0xffff0000, v243
	v_mul_f32_e32 v53, v34, v52
	v_mul_f32_e32 v54, v35, v52
	v_mul_f32_e32 v55, v36, v52
	v_mul_f32_e32 v56, v37, v52
	v_mul_f32_e32 v53, v53, v57
	v_mul_f32_e32 v54, v54, v58
	v_mul_f32_e32 v55, v55, v59
	v_mul_f32_e32 v56, v56, v60
	v_cvt_pk_bf16_f32 v250, v53, v54
	v_cvt_pk_bf16_f32 v251, v55, v56
	global_store_dwordx2 v[50:51], v[250:251], off offset:320
	s_waitcnt vmcnt(31)
	v_lshlrev_b32_e32 v57, 16, v244
	v_and_b32_e32 v58, 0xffff0000, v244
	v_lshlrev_b32_e32 v59, 16, v245
	v_and_b32_e32 v60, 0xffff0000, v245
	v_mul_f32_e32 v53, v38, v52
	v_mul_f32_e32 v54, v39, v52
	v_mul_f32_e32 v55, v40, v52
	v_mul_f32_e32 v56, v41, v52
	v_mul_f32_e32 v53, v53, v57
	v_mul_f32_e32 v54, v54, v58
	v_mul_f32_e32 v55, v55, v59
	v_mul_f32_e32 v56, v56, v60
	v_cvt_pk_bf16_f32 v252, v53, v54
	v_cvt_pk_bf16_f32 v253, v55, v56
	global_store_dwordx2 v[50:51], v[252:253], off offset:336
	s_waitcnt vmcnt(31)
	v_lshlrev_b32_e32 v57, 16, v246
	v_and_b32_e32 v58, 0xffff0000, v246
	v_lshlrev_b32_e32 v59, 16, v247
	v_and_b32_e32 v60, 0xffff0000, v247
	v_mul_f32_e32 v53, v42, v52
	v_mul_f32_e32 v54, v43, v52
	v_mul_f32_e32 v55, v44, v52
	v_mul_f32_e32 v56, v45, v52
	v_mul_f32_e32 v53, v53, v57
	v_mul_f32_e32 v54, v54, v58
	v_mul_f32_e32 v55, v55, v59
	v_mul_f32_e32 v56, v56, v60
	v_cvt_pk_bf16_f32 v250, v53, v54
	v_cvt_pk_bf16_f32 v251, v55, v56
	global_store_dwordx2 v[50:51], v[250:251], off offset:352
	s_waitcnt vmcnt(31)
; __device__ __forceinline__ unsigned cvtpk(float lo, float hi) { return pg8::cvt_pk_bf16(lo, hi); }
;     ...
;           for (int et = 0; et < 8; ++et)
; #pragma unroll
;               for (int i4 = 0; i4 < 4; ++i4) { bf16* p4 = gp + 32 * et + 8 * i4; const v2u gg = *(const v2u*)p4;
;                   v2u wv; wv.x = cvtpk(acc[et][4 * i4] * rstd * __uint_as_float(gg.x << 16), acc[et][4 * i4 + 1] * rstd * __uint_as_float(gg.x & 0xffff0000u));
;                   wv.y = cvtpk(acc[et][4 * i4 + 2] * rstd * __uint_as_float(gg.y << 16), acc[et][4 * i4 + 3] * rstd * __uint_as_float(gg.y & 0xffff0000u));
;                   if (!dry || rstd == 1.2345e38f) *(v2u*)p4 = wv; if (i4 == 3 && (et & 1)) asm volatile("" ::: "memory"); } }
	v_lshlrev_b32_e32 v57, 16, v248
	v_and_b32_e32 v58, 0xffff0000, v248
	v_lshlrev_b32_e32 v59, 16, v249
	v_and_b32_e32 v60, 0xffff0000, v249
	v_mul_f32_e32 v53, v46, v52
	v_mul_f32_e32 v54, v47, v52
	v_mul_f32_e32 v55, v48, v52
	v_mul_f32_e32 v56, v49, v52
	v_mul_f32_e32 v53, v53, v57
	v_mul_f32_e32 v54, v54, v58
	v_mul_f32_e32 v55, v55, v59
	v_mul_f32_e32 v56, v56, v60
	v_cvt_pk_bf16_f32 v252, v53, v54
	v_cvt_pk_bf16_f32 v253, v55, v56
	global_store_dwordx2 v[50:51], v[252:253], off offset:368
	s_waitcnt vmcnt(30)
	v_lshlrev_b32_e32 v57, 16, v82
	v_and_b32_e32 v58, 0xffff0000, v82
	v_lshlrev_b32_e32 v59, 16, v83
	v_and_b32_e32 v60, 0xffff0000, v83
	v_mul_f32_e32 v53, v16, v52
	v_mul_f32_e32 v54, v17, v52
	v_mul_f32_e32 v55, v18, v52
	v_mul_f32_e32 v56, v19, v52
	v_mul_f32_e32 v53, v53, v57
	v_mul_f32_e32 v54, v54, v58
	v_mul_f32_e32 v55, v55, v59
	v_mul_f32_e32 v56, v56, v60
	v_cvt_pk_bf16_f32 v250, v53, v54
	v_cvt_pk_bf16_f32 v251, v55, v56
	global_store_dwordx2 v[50:51], v[250:251], off offset:384
	s_waitcnt vmcnt(29)
	v_lshlrev_b32_e32 v57, 16, v84
	v_and_b32_e32 v58, 0xffff0000, v84
	v_lshlrev_b32_e32 v59, 16, v85
	v_and_b32_e32 v60, 0xffff0000, v85
	v_mul_f32_e32 v53, v20, v52
	v_mul_f32_e32 v54, v21, v52
	v_mul_f32_e32 v55, v22, v52
	v_mul_f32_e32 v56, v23, v52
	v_mul_f32_e32 v53, v53, v57
	v_mul_f32_e32 v54, v54, v58
	v_mul_f32_e32 v55, v55, v59
	v_mul_f32_e32 v56, v56, v60
	v_cvt_pk_bf16_f32 v252, v53, v54
	v_cvt_pk_bf16_f32 v253, v55, v56
	global_store_dwordx2 v[50:51], v[252:253], off offset:400
	s_waitcnt vmcnt(28)
	v_lshlrev_b32_e32 v57, 16, v86
	v_and_b32_e32 v58, 0xffff0000, v86
	v_lshlrev_b32_e32 v59, 16, v87
	v_and_b32_e32 v60, 0xffff0000, v87
	v_mul_f32_e32 v53, v24, v52
	v_mul_f32_e32 v54, v25, v52
	v_mul_f32_e32 v55, v26, v52
	v_mul_f32_e32 v56, v27, v52
	v_mul_f32_e32 v53, v53, v57
	v_mul_f32_e32 v54, v54, v58
	v_mul_f32_e32 v55, v55, v59
	v_mul_f32_e32 v56, v56, v60
	v_cvt_pk_bf16_f32 v250, v53, v54
	v_cvt_pk_bf16_f32 v251, v55, v56
	global_store_dwordx2 v[50:51], v[250:251], off offset:416
	s_waitcnt vmcnt(27)
	v_lshlrev_b32_e32 v57, 16, v88
	v_and_b32_e32 v58, 0xffff0000, v88
	v_lshlrev_b32_e32 v59, 16, v89
	v_and_b32_e32 v60, 0xffff0000, v89
	v_mul_f32_e32 v53, v28, v52
	v_mul_f32_e32 v54, v29, v52
	v_mul_f32_e32 v55, v30, v52
	v_mul_f32_e32 v56, v31, v52
	v_mul_f32_e32 v53, v53, v57
	v_mul_f32_e32 v54, v54, v58
	v_mul_f32_e32 v55, v55, v59
	v_mul_f32_e32 v56, v56, v60
	v_cvt_pk_bf16_f32 v252, v53, v54
	v_cvt_pk_bf16_f32 v253, v55, v56
	global_store_dwordx2 v[50:51], v[252:253], off offset:432
	s_waitcnt vmcnt(26)
	v_lshlrev_b32_e32 v57, 16, v90
	v_and_b32_e32 v58, 0xffff0000, v90
	v_lshlrev_b32_e32 v59, 16, v91
	v_and_b32_e32 v60, 0xffff0000, v91
	v_mul_f32_e32 v53, v0, v52
	v_mul_f32_e32 v54, v1, v52
	v_mul_f32_e32 v55, v2, v52
	v_mul_f32_e32 v56, v3, v52
	v_mul_f32_e32 v53, v53, v57
	v_mul_f32_e32 v54, v54, v58
	v_mul_f32_e32 v55, v55, v59
	v_mul_f32_e32 v56, v56, v60
	v_cvt_pk_bf16_f32 v250, v53, v54
	v_cvt_pk_bf16_f32 v251, v55, v56
	global_store_dwordx2 v[50:51], v[250:251], off offset:448
	s_waitcnt vmcnt(25)
	v_lshlrev_b32_e32 v57, 16, v92
	v_and_b32_e32 v58, 0xffff0000, v92
	v_lshlrev_b32_e32 v59, 16, v93
	v_and_b32_e32 v60, 0xffff0000, v93
	v_mul_f32_e32 v53, v4, v52
	v_mul_f32_e32 v54, v5, v52
	v_mul_f32_e32 v55, v6, v52
	v_mul_f32_e32 v56, v7, v52
	v_mul_f32_e32 v53, v53, v57
	v_mul_f32_e32 v54, v54, v58
	v_mul_f32_e32 v55, v55, v59
	v_mul_f32_e32 v56, v56, v60
	v_cvt_pk_bf16_f32 v252, v53, v54
	v_cvt_pk_bf16_f32 v253, v55, v56
	global_store_dwordx2 v[50:51], v[252:253], off offset:464
	s_waitcnt vmcnt(24)
	v_lshlrev_b32_e32 v57, 16, v204
	v_and_b32_e32 v58, 0xffff0000, v204
	v_lshlrev_b32_e32 v59, 16, v205
	v_and_b32_e32 v60, 0xffff0000, v205
	v_mul_f32_e32 v53, v8, v52
	v_mul_f32_e32 v54, v9, v52
	v_mul_f32_e32 v55, v10, v52
	v_mul_f32_e32 v56, v11, v52
	v_mul_f32_e32 v53, v53, v57
	v_mul_f32_e32 v54, v54, v58
	v_mul_f32_e32 v55, v55, v59
	v_mul_f32_e32 v56, v56, v60
	v_cvt_pk_bf16_f32 v250, v53, v54
	v_cvt_pk_bf16_f32 v251, v55, v56
	global_store_dwordx2 v[50:51], v[250:251], off offset:480
	s_waitcnt vmcnt(23)
	v_lshlrev_b32_e32 v57, 16, v206
	v_and_b32_e32 v58, 0xffff0000, v206
	v_lshlrev_b32_e32 v59, 16, v207
	v_and_b32_e32 v60, 0xffff0000, v207
	v_mul_f32_e32 v53, v12, v52
	v_mul_f32_e32 v54, v13, v52
	v_mul_f32_e32 v55, v14, v52
	v_mul_f32_e32 v56, v15, v52
	v_mul_f32_e32 v53, v53, v57
	v_mul_f32_e32 v54, v54, v58
	v_mul_f32_e32 v55, v55, v59
	v_mul_f32_e32 v56, v56, v60
	v_cvt_pk_bf16_f32 v252, v53, v54
	v_cvt_pk_bf16_f32 v253, v55, v56
	global_store_dwordx2 v[50:51], v[252:253], off offset:496
	s_cbranch_scc0 .LBB0_734
